# baseline (speedup 1.0000x reference)
; __device__ __forceinline__ float h2f(unsigned h) { float r; asm volatile("v_cvt_f32_f16 %0, %1" : "=v"(r) : "v"(h)); return r; }
; #define PG8_WAIT_V(n) asm volatile("s_waitcnt vmcnt(" #n ")" ::: "memory")
; #define PG8_BAR __builtin_amdgcn_s_barrier()
; template <class Epi, class Sched, bool FUSED = false, bool APERM = false>
; __device__ __forceinline__ void gemm_phase(int wid_s, LAS unsigned char* lds, const Gemm g, const Sched& S, const Epi& E) {
;     ...
;     PG8_WAIT_V(0);
;     PG8_BAR;
;     if constexpr (FUSED) { int efr = fr, efq = fq; asm volatile("" : "+v"(efr), "+v"(efq)); E.fused(acc, cur, wr, wc, efr, efq, lds, wid); }
;     __device__ __forceinline__ void fused(f32x4 (&acc)[2][2][4][2], const pg8::Unit& u, int wr, int wc, int fr, int fq, LAS unsigned char* lds, int wid) const {
;     ...
;                     for (int n = 0; n < 2; ++n) xr[ai][m][bj][n] = *(const u32x2*)(X + (size_t)(u.pm * 256 + rl0 + ai * 128 + m * 16) * DM + col0 + 128 * bj + 4 * n);
; #pragma unroll
;         for (int ai = 0; ai < 2; ++ai)
; #pragma unroll
;             for (int m = 0; m < 4; ++m) {
;                 const int rl = rl0 + ai * 128 + m * 16; float s = 0.f, q = 0.f;
; #pragma unroll
;                 for (int bj = 0; bj < 2; ++bj)
; #pragma unroll
;                     for (int n = 0; n < 2; ++n) {
;                         const u32x2 xw = xr[ai][m][bj][n];
;                         const f32x4 x = {h2f(xw.x), h2f(xw.x >> 16), h2f(xw.y), h2f(xw.y >> 16)};
;                         const f32x4 z = x * ALPHA + acc[ai][bj][m][n]; acc[ai][bj][m][n] = z;
;                         s += (z[0] + z[1]) + (z[2] + z[3]); q += (z[0] * z[0] + z[1] * z[1]) + (z[2] * z[2] + z[3] * z[3]);
;                     }
;                 s += __shfl_xor(s, 16); s += __shfl_xor(s, 32); q += __shfl_xor(q, 16); q += __shfl_xor(q, 32);
;                 if (fq == 0) P[rl * 4 + wc] = (f32x2){s, q};
.LBB0_662:
	s_lshl_b32 s0, s10, 5
	s_lshl_b32 s1, s16, 8
	s_or_b32 s0, s1, s0
	s_lshl_b32 s2, s14, 8
	v_add_u32_e32 v222, s53, v221
	v_lshl_add_u32 v212, v220, 3, s0
	v_add_u32_e32 v0, s2, v222
	v_ashrrev_i32_e32 v213, 31, v212
	v_lshl_add_u64 v[132:133], v[212:213], 1, s[18:19]
	s_mov_b64 s[0:1], 0x14e00000
	v_ashrrev_i32_e32 v1, 31, v0
	v_lshl_add_u64 v[132:133], v[132:133], 0, s[0:1]
	v_lshlrev_b64 v[216:217], 12, v[0:1]
	v_lshl_add_u64 v[0:1], v[132:133], 0, v[216:217]
	flat_load_dwordx4 v[224:227], v[0:1]
	flat_load_dwordx4 v[228:231], v[0:1] offset:256
	s_mov_b64 s[0:1], 0x10000
	v_lshl_add_u64 v[214:215], v[216:217], 0, s[0:1]
	s_mov_b64 s[0:1], 0x20000
	v_lshl_add_u64 v[210:211], v[216:217], 0, s[0:1]
	s_mov_b64 s[0:1], 0x30000
	v_lshl_add_u64 v[208:209], v[216:217], 0, s[0:1]
	s_mov_b64 s[0:1], 0x80000
	v_lshl_add_u64 v[194:195], v[216:217], 0, s[0:1]
	s_mov_b64 s[0:1], 0x90000
	v_lshl_add_u64 v[192:193], v[216:217], 0, s[0:1]
	s_mov_b64 s[0:1], 0xa0000
	v_lshl_add_u64 v[190:191], v[216:217], 0, s[0:1]
	s_mov_b64 s[0:1], 0xb0000
	v_lshl_add_u64 v[188:189], v[216:217], 0, s[0:1]
	v_lshl_add_u64 v[0:1], v[132:133], 0, v[214:215]
	v_lshl_add_u64 v[134:135], v[132:133], 0, v[210:211]
	v_lshl_add_u64 v[136:137], v[132:133], 0, v[208:209]
	v_lshl_add_u64 v[138:139], v[132:133], 0, v[194:195]
	v_lshl_add_u64 v[140:141], v[132:133], 0, v[192:193]
	v_lshl_add_u64 v[142:143], v[132:133], 0, v[190:191]
	v_lshl_add_u64 v[132:133], v[132:133], 0, v[188:189]
	flat_load_dwordx4 v[184:187], v[0:1]
	flat_load_dwordx4 v[180:183], v[0:1] offset:256
	flat_load_dwordx4 v[176:179], v[134:135]
	flat_load_dwordx4 v[172:175], v[134:135] offset:256
	flat_load_dwordx4 v[168:171], v[136:137]
	flat_load_dwordx4 v[164:167], v[136:137] offset:256
	flat_load_dwordx4 v[160:163], v[138:139]
	flat_load_dwordx4 v[156:159], v[138:139] offset:256
	flat_load_dwordx4 v[152:155], v[140:141]
	flat_load_dwordx4 v[148:151], v[140:141] offset:256
	flat_load_dwordx4 v[144:147], v[142:143]
	s_nop 0
	flat_load_dwordx4 v[140:143], v[142:143] offset:256
	s_nop 0
	flat_load_dwordx4 v[136:139], v[132:133]
	s_nop 0
	flat_load_dwordx4 v[132:135], v[132:133] offset:256
	s_mov_b32 s0, 0x3fd744fd
	v_mov_b64_e32 v[202:203], 0x80
	s_waitcnt vmcnt(0)
	s_barrier
	s_waitcnt vmcnt(0) lgkmcnt(0)
	v_cvt_f32_f16 v0, v224
	v_lshrrev_b32_e32 v1, 16, v224
	v_lshrrev_b32_e32 v3, 16, v225
	v_lshrrev_b32_e32 v200, 16, v226
	v_lshrrev_b32_e32 v201, 16, v227
	v_lshrrev_b32_e32 v234, 16, v229
	v_lshrrev_b32_e32 v235, 16, v230
	v_cvt_f32_f16 v1, v1
	v_cvt_f32_f16 v218, v225
	v_cvt_f32_f16 v219, v3
	v_cvt_f32_f16 v224, v226
	v_cvt_f32_f16 v225, v200
	v_cvt_f32_f16 v226, v227
	v_cvt_f32_f16 v227, v201
	s_nop 0
	v_pk_fma_f32 v[128:129], v[0:1], s[0:1], v[128:129] op_sel_hi:[1,0,1]
	v_pk_fma_f32 v[126:127], v[226:227], s[0:1], v[126:127] op_sel_hi:[1,0,1]
	v_lshrrev_b32_e32 v223, 16, v228
	v_lshrrev_b32_e32 v236, 16, v231
	v_cvt_f32_f16 v232, v228
	v_cvt_f32_f16 v233, v223
	v_cvt_f32_f16 v228, v229
	v_cvt_f32_f16 v229, v234
	v_cvt_f32_f16 v234, v230
	v_cvt_f32_f16 v235, v235
	v_cvt_f32_f16 v230, v231
	v_cvt_f32_f16 v231, v236
	v_pk_fma_f32 v[130:131], v[218:219], s[0:1], v[130:131] op_sel_hi:[1,0,1]
	v_pk_fma_f32 v[124:125], v[224:225], s[0:1], v[124:125] op_sel_hi:[1,0,1]
	v_mul_f32_e32 v225, v128, v128
	v_mul_f32_e32 v224, v126, v126
	v_pk_fma_f32 v[122:123], v[228:229], s[0:1], v[122:123] op_sel_hi:[1,0,1]
	v_pk_fma_f32 v[238:239], v[230:231], s[0:1], v[118:119] op_sel_hi:[1,0,1]
	v_add_f32_e32 v118, v128, v129
	v_add_f32_e32 v218, v130, v131
	v_mul_f32_e32 v227, v129, v129
	v_mul_f32_e32 v229, v130, v130
	v_mul_f32_e32 v231, v131, v131
	v_mul_f32_e32 v119, v124, v124
	v_mul_f32_e32 v219, v125, v125
	v_pk_fma_f32 v[246:247], v[126:127], v[126:127], v[224:225] op_sel_hi:[1,1,0]
	v_and_b32_e32 v3, 64, v240
	v_mov_b32_e32 v224, v124
	v_mov_b32_e32 v226, v125
	v_mov_b32_e32 v228, v126
	v_mov_b32_e32 v230, v127
	v_pk_fma_f32 v[120:121], v[232:233], s[0:1], v[120:121] op_sel_hi:[1,0,1]
	v_xor_b32_e32 v0, 16, v240
	v_add_u32_e32 v243, 64, v3
	v_pk_add_f32 v[224:225], v[224:225], v[226:227]
	v_pk_add_f32 v[226:227], v[228:229], v[230:231]
	v_pk_add_f32 v[118:119], v[118:119], v[218:219]
	v_mov_b32_e32 v3, v247
	v_pk_fma_f32 v[116:117], v[234:235], s[0:1], v[116:117] op_sel_hi:[1,0,1]
	v_mul_f32_e32 v233, v120, v120
	v_mul_f32_e32 v235, v121, v121
	v_mul_f32_e32 v237, v122, v122
	v_mul_f32_e32 v245, v123, v123
	v_cmp_lt_i32_e32 vcc, v0, v243
	v_pk_add_f32 v[224:225], v[224:225], v[226:227]
	v_pk_add_f32 v[118:119], v[118:119], v[2:3]
	v_mov_b32_e32 v232, v120
	v_mov_b32_e32 v234, v121
	v_mov_b32_e32 v236, v122
	v_mov_b32_e32 v244, v123
	v_cndmask_b32_e32 v0, v240, v0, vcc
	v_pk_add_f32 v[118:119], v[224:225], v[118:119]
	v_pk_add_f32 v[218:219], v[232:233], v[234:235]
	v_pk_add_f32 v[224:225], v[236:237], v[244:245]
	v_mul_f32_e32 v249, v116, v116
	v_mul_f32_e32 v251, v117, v117
	v_mul_f32_e32 v1, v238, v238
	v_mul_f32_e32 v201, v239, v239
	v_lshlrev_b32_e32 v223, 2, v0
	v_pk_add_f32 v[218:219], v[218:219], v[224:225]
	v_mov_b32_e32 v248, v116
	v_mov_b32_e32 v250, v117
	v_mov_b32_e32 v0, v238
	v_mov_b32_e32 v200, v239
	v_pk_add_f32 v[118:119], v[118:119], v[218:219]
	v_pk_add_f32 v[218:219], v[248:249], v[250:251]
	v_pk_add_f32 v[0:1], v[0:1], v[200:201]
	v_xor_b32_e32 v3, 32, v240
	v_pk_add_f32 v[0:1], v[218:219], v[0:1]
	v_cmp_lt_i32_e32 vcc, v3, v243
	v_pk_add_f32 v[0:1], v[118:119], v[0:1]
	ds_bpermute_b32 v118, v223, v0
	ds_bpermute_b32 v119, v223, v1
	v_cndmask_b32_e32 v3, v240, v3, vcc
	v_lshlrev_b32_e32 v225, 2, v3
	s_lshl_b32 s0, s10, 3
	s_add_i32 s0, s0, 0
	s_waitcnt lgkmcnt(0)
	v_pk_add_f32 v[118:119], v[0:1], v[118:119]
	ds_bpermute_b32 v218, v225, v118
	ds_bpermute_b32 v219, v225, v119
	v_cmp_eq_u32_e32 vcc, 0, v220
	v_lshl_add_u32 v224, v222, 5, s0
	s_and_saveexec_b64 s[0:1], vcc
	s_cbranch_execz .LBB0_664
	s_waitcnt lgkmcnt(0)
	v_pk_add_f32 v[0:1], v[118:119], v[218:219]
	ds_write_b64 v224, v[0:1]

; __device__ __forceinline__ float h2f(unsigned h) { float r; asm volatile("v_cvt_f32_f16 %0, %1" : "=v"(r) : "v"(h)); return r; }
; #define PG8_WAIT_V(n) asm volatile("s_waitcnt vmcnt(" #n ")" ::: "memory")
; #define PG8_BAR __builtin_amdgcn_s_barrier()
; template <class Epi, class Sched, bool FUSED = false, bool APERM = false>
; __device__ __forceinline__ void gemm_phase(int wid_s, LAS unsigned char* lds, const Gemm g, const Sched& S, const Epi& E) {
;     ...
;     PG8_WAIT_V(0);
;     PG8_BAR;
;     if constexpr (FUSED) { int efr = fr, efq = fq; asm volatile("" : "+v"(efr), "+v"(efq)); E.fused(acc, cur, wr, wc, efr, efq, lds, wid); }
;     __device__ __forceinline__ void fused(f32x4 (&acc)[2][2][4][2], const pg8::Unit& u, int wr, int wc, int fr, int fq, LAS unsigned char* lds, int wid) const {
;     ...
;                     for (int n = 0; n < 2; ++n) xr[ai][m][bj][n] = *(const u32x2*)(X + (size_t)(u.pm * 256 + rl0 + ai * 128 + m * 16) * DM + col0 + 128 * bj + 4 * n);
; #pragma unroll
;         for (int ai = 0; ai < 2; ++ai)
; #pragma unroll
;             for (int m = 0; m < 4; ++m) {
;                 const int rl = rl0 + ai * 128 + m * 16; float s = 0.f, q = 0.f;
; #pragma unroll
;                 for (int bj = 0; bj < 2; ++bj)
; #pragma unroll
;                     for (int n = 0; n < 2; ++n) {
;                         const u32x2 xw = xr[ai][m][bj][n];
;                         const f32x4 x = {h2f(xw.x), h2f(xw.x >> 16), h2f(xw.y), h2f(xw.y >> 16)};
;                         const f32x4 z = x * ALPHA + acc[ai][bj][m][n]; acc[ai][bj][m][n] = z;
;                         s += (z[0] + z[1]) + (z[2] + z[3]); q += (z[0] * z[0] + z[1] * z[1]) + (z[2] * z[2] + z[3] * z[3]);
;                     }
;                 s += __shfl_xor(s, 16); s += __shfl_xor(s, 32); q += __shfl_xor(q, 16); q += __shfl_xor(q, 32);
;                 if (fq == 0) P[rl * 4 + wc] = (f32x2){s, q};
.LBB0_938:
	s_lshl_b32 s0, s10, 5
	s_lshl_b32 s1, s20, 8
	s_or_b32 s0, s1, s0
	s_lshl_b32 s2, s41, 8
	v_add_u32_e32 v222, s53, v221
	v_lshl_add_u32 v0, v220, 3, s0
	v_add_u32_e32 v214, s2, v222
	v_ashrrev_i32_e32 v1, 31, v0
	v_lshl_add_u64 v[132:133], v[0:1], 1, s[22:23]
	s_mov_b64 s[0:1], 0x14e00000
	v_ashrrev_i32_e32 v215, 31, v214
	v_lshl_add_u64 v[132:133], v[132:133], 0, s[0:1]
	v_lshlrev_b64 v[134:135], 12, v[214:215]
	v_lshl_add_u64 v[134:135], v[132:133], 0, v[134:135]
	flat_load_dwordx4 v[216:219], v[134:135]
	flat_load_dwordx4 v[224:227], v[134:135] offset:256
	v_add_u32_e32 v212, 16, v214
	v_add_u32_e32 v210, 32, v214
	v_add_u32_e32 v208, 48, v214
	v_add_u32_e32 v194, 0x80, v214
	v_add_u32_e32 v192, 0x90, v214
	v_add_u32_e32 v190, 0xa0, v214
	v_add_u32_e32 v188, 0xb0, v214
	v_ashrrev_i32_e32 v213, 31, v212
	v_ashrrev_i32_e32 v211, 31, v210
	v_ashrrev_i32_e32 v209, 31, v208
	v_ashrrev_i32_e32 v195, 31, v194
	v_ashrrev_i32_e32 v193, 31, v192
	v_ashrrev_i32_e32 v191, 31, v190
	v_ashrrev_i32_e32 v189, 31, v188
	v_lshlrev_b64 v[134:135], 12, v[212:213]
	v_lshlrev_b64 v[136:137], 12, v[210:211]
	v_lshlrev_b64 v[138:139], 12, v[208:209]
	v_lshlrev_b64 v[140:141], 12, v[194:195]
	v_lshlrev_b64 v[142:143], 12, v[192:193]
	v_lshlrev_b64 v[144:145], 12, v[190:191]
	v_lshlrev_b64 v[146:147], 12, v[188:189]
	v_lshl_add_u64 v[134:135], v[132:133], 0, v[134:135]
	v_lshl_add_u64 v[136:137], v[132:133], 0, v[136:137]
	v_lshl_add_u64 v[138:139], v[132:133], 0, v[138:139]
	v_lshl_add_u64 v[140:141], v[132:133], 0, v[140:141]
	v_lshl_add_u64 v[142:143], v[132:133], 0, v[142:143]
	v_lshl_add_u64 v[200:201], v[132:133], 0, v[144:145]
	v_lshl_add_u64 v[132:133], v[132:133], 0, v[146:147]
	flat_load_dwordx4 v[184:187], v[134:135]
	flat_load_dwordx4 v[180:183], v[134:135] offset:256
	flat_load_dwordx4 v[176:179], v[136:137]
	flat_load_dwordx4 v[172:175], v[136:137] offset:256
	flat_load_dwordx4 v[168:171], v[138:139]
	flat_load_dwordx4 v[164:167], v[138:139] offset:256
	flat_load_dwordx4 v[160:163], v[140:141]
	flat_load_dwordx4 v[156:159], v[140:141] offset:256
	flat_load_dwordx4 v[152:155], v[142:143]
	flat_load_dwordx4 v[148:151], v[142:143] offset:256
	flat_load_dwordx4 v[144:147], v[200:201]
	s_nop 0
	flat_load_dwordx4 v[140:143], v[200:201] offset:256
	flat_load_dwordx4 v[136:139], v[132:133]
	s_nop 0
	flat_load_dwordx4 v[132:135], v[132:133] offset:256
	s_mov_b32 s0, 0x3fd744fd
	v_mov_b64_e32 v[202:203], 0x80
	s_waitcnt vmcnt(0)
	s_barrier
	s_waitcnt vmcnt(0) lgkmcnt(0)
	v_cvt_f32_f16 v200, v216
	v_lshrrev_b32_e32 v229, 16, v218
	v_lshrrev_b32_e32 v3, 16, v216
	v_lshrrev_b32_e32 v223, 16, v217
	v_lshrrev_b32_e32 v230, 16, v219
	v_cvt_f32_f16 v201, v3
	v_cvt_f32_f16 v216, v217
	v_cvt_f32_f16 v217, v223
	v_cvt_f32_f16 v228, v218
	v_cvt_f32_f16 v229, v229
	v_cvt_f32_f16 v218, v219
	v_cvt_f32_f16 v219, v230
	s_nop 0
	v_pk_fma_f32 v[128:129], v[200:201], s[0:1], v[128:129] op_sel_hi:[1,0,1]
	v_pk_fma_f32 v[126:127], v[218:219], s[0:1], v[126:127] op_sel_hi:[1,0,1]
	v_lshrrev_b32_e32 v231, 16, v224
	v_mul_f32_e32 v219, v128, v128
	v_mul_f32_e32 v218, v126, v126
	v_lshrrev_b32_e32 v3, 16, v226
	v_lshrrev_b32_e32 v232, 16, v225
	v_cvt_f32_f16 v230, v224
	v_cvt_f32_f16 v231, v231
	v_cvt_f32_f16 v224, v225
	v_cvt_f32_f16 v225, v232
	v_pk_fma_f32 v[236:237], v[126:127], v[126:127], v[218:219] op_sel_hi:[1,1,0]
	v_cvt_f32_f16 v246, v226
	v_cvt_f32_f16 v247, v3
	v_lshrrev_b32_e32 v3, 16, v227
	v_and_b32_e32 v218, 64, v240
	v_cvt_f32_f16 v226, v227
	v_cvt_f32_f16 v227, v3
	v_xor_b32_e32 v3, 16, v240
	v_add_u32_e32 v236, 64, v218
	v_pk_fma_f32 v[130:131], v[216:217], s[0:1], v[130:131] op_sel_hi:[1,0,1]
	v_pk_fma_f32 v[124:125], v[228:229], s[0:1], v[124:125] op_sel_hi:[1,0,1]
	v_cmp_lt_i32_e32 vcc, v3, v236
	v_add_f32_e32 v200, v128, v129
	v_add_f32_e32 v216, v130, v131
	v_mul_f32_e32 v229, v129, v129
	v_mul_f32_e32 v233, v130, v130
	v_mul_f32_e32 v235, v131, v131
	v_mul_f32_e32 v201, v124, v124
	v_mul_f32_e32 v217, v125, v125
	v_cndmask_b32_e32 v3, v240, v3, vcc
	v_mov_b32_e32 v218, v124
	v_mov_b32_e32 v228, v125
	v_mov_b32_e32 v232, v126
	v_mov_b32_e32 v234, v127
	v_pk_fma_f32 v[122:123], v[224:225], s[0:1], v[122:123] op_sel_hi:[1,0,1]
	v_pk_fma_f32 v[120:121], v[230:231], s[0:1], v[120:121] op_sel_hi:[1,0,1]
	v_lshlrev_b32_e32 v223, 2, v3
	v_pk_add_f32 v[218:219], v[218:219], v[228:229]
	v_pk_add_f32 v[228:229], v[232:233], v[234:235]
	v_pk_add_f32 v[200:201], v[200:201], v[216:217]
	v_mov_b32_e32 v3, v237
	v_mul_f32_e32 v225, v120, v120
	v_mul_f32_e32 v231, v121, v121
	v_mul_f32_e32 v239, v122, v122
	v_mul_f32_e32 v245, v123, v123
	v_pk_add_f32 v[218:219], v[218:219], v[228:229]
	v_pk_add_f32 v[200:201], v[200:201], v[2:3]
	v_mov_b32_e32 v224, v120
	v_mov_b32_e32 v230, v121
	v_mov_b32_e32 v238, v122
	v_mov_b32_e32 v244, v123
	v_pk_fma_f32 v[118:119], v[226:227], s[0:1], v[118:119] op_sel_hi:[1,0,1]
	v_pk_fma_f32 v[116:117], v[246:247], s[0:1], v[116:117] op_sel_hi:[1,0,1]
	v_pk_add_f32 v[200:201], v[218:219], v[200:201]
	v_pk_add_f32 v[216:217], v[224:225], v[230:231]
	v_pk_add_f32 v[218:219], v[238:239], v[244:245]
	v_mul_f32_e32 v227, v116, v116
	v_mul_f32_e32 v247, v117, v117
	v_mul_f32_e32 v249, v118, v118
	v_mul_f32_e32 v251, v119, v119
	v_pk_add_f32 v[216:217], v[216:217], v[218:219]
	v_mov_b32_e32 v226, v116
	v_mov_b32_e32 v246, v117
	v_mov_b32_e32 v248, v118
	v_mov_b32_e32 v250, v119
	v_pk_add_f32 v[200:201], v[200:201], v[216:217]
	v_pk_add_f32 v[216:217], v[226:227], v[246:247]
	v_pk_add_f32 v[218:219], v[248:249], v[250:251]
	v_xor_b32_e32 v3, 32, v240
	v_pk_add_f32 v[216:217], v[216:217], v[218:219]
	v_cmp_lt_i32_e32 vcc, v3, v236
	v_pk_add_f32 v[200:201], v[200:201], v[216:217]
	ds_bpermute_b32 v216, v223, v200
	ds_bpermute_b32 v217, v223, v201
	v_cndmask_b32_e32 v3, v240, v3, vcc
	v_lshlrev_b32_e32 v225, 2, v3
	s_lshl_b32 s0, s10, 3
	s_add_i32 s0, s0, 0
	s_waitcnt lgkmcnt(0)
	v_pk_add_f32 v[216:217], v[200:201], v[216:217]
	ds_bpermute_b32 v218, v225, v216
	ds_bpermute_b32 v219, v225, v217
	v_cmp_eq_u32_e32 vcc, 0, v220
	v_lshl_add_u32 v224, v222, 5, s0
	s_and_saveexec_b64 s[0:1], vcc
	s_cbranch_execz .LBB0_940
	s_waitcnt lgkmcnt(0)
	v_pk_add_f32 v[200:201], v[216:217], v[218:219]
	ds_write_b64 v224, v[200:201]
